# grid barrier: removed the now-unread per-XCD generation atomic (and its ~1us vmcnt wait) from the XCD leader's release path, on top of v21
# speedup vs baseline: 1.0009x; 1.0009x over previous
; __device__ __forceinline__ unsigned xb_ld(unsigned* p)              { return __hip_atomic_load(p, __ATOMIC_RELAXED, __HIP_MEMORY_SCOPE_AGENT); }
; __device__ __forceinline__ unsigned xb_add(unsigned* p, unsigned v) { return __hip_atomic_fetch_add(p, v, __ATOMIC_RELAXED, __HIP_MEMORY_SCOPE_AGENT); }
; #define XB_SPIN(cond, bar) do { unsigned _sp = 0; while (cond) { __builtin_amdgcn_s_sleep(1); \
;     if ((++_sp & 255u) == 0u) { if (xb_ld(&(bar)[XB_TMO])) break; if (_sp > XB_SPIN_CAP) { atomicAdd(&(bar)[XB_TMO], 1u); break; } } } } while (0)
; __device__ __forceinline__ void xcd_barrier(const XcdBarrier& b) {
;     ...
;             const unsigned og = xb_add(&bar[XB_TOP], 1u);
;             const unsigned tg = og / nx;
;             if (og + 1u == (tg + 1u) * nx) xb_add(&bar[XB_TOPGEN], 1u);
;             else XB_SPIN(xb_ld(&bar[XB_TOPGEN]) == tg, bar);
;             __builtin_amdgcn_fence(__ATOMIC_ACQUIRE, "agent");
;             xb_add(&bar[XB_XGEN(b.x)], 1u);
;             asm volatile("s_waitcnt vmcnt(0)" ::: "memory");
.LBB0_1123:
	s_bcnt1_i32_b64 s16, s[16:17]
	v_mov_b32_e32 v0, s16
	v_readlane_b32 s16, v254, 30
	v_readlane_b32 s17, v254, 31
	s_nop 4
	s_getpc_b64 s[98:99]
